# grid barrier: both the XCD leader and the other workgroups issue their L1 invalidate before they start polling (leader: right after its arrival on the top counter)
# speedup vs baseline: 1.0092x; 1.0092x over previous
; DI unsigned xb_ld(unsigned* p)              { return __hip_atomic_load(p, __ATOMIC_RELAXED, __HIP_MEMORY_SCOPE_AGENT); }
; DI unsigned xb_add(unsigned* p, unsigned v) { return __hip_atomic_fetch_add(p, v, __ATOMIC_RELAXED, __HIP_MEMORY_SCOPE_AGENT); }
; #define XB_SPIN(cond, bar) do { unsigned _sp = 0; while (cond) { __builtin_amdgcn_s_sleep(1); \
;     if ((++_sp & 255u) == 0u) { if (xb_ld(&(bar)[XB_TMO])) break; if (_sp > XB_SPIN_CAP) { atomicAdd(&(bar)[XB_TMO], 1u); break; } } } } while (0)
; DI void xcd_barrier(const XcdBarrier& b) {
;     ...
;             const unsigned og = xb_add(&bar[XB_TOP], 1u);
;             const unsigned tg = og / nx;
;             if (og + 1u == (tg + 1u) * nx) xb_add(&bar[XB_TOPGEN], 1u);
;             else XB_SPIN(xb_ld(&bar[XB_TOPGEN]) == tg, bar);
.LBB0_158:
	s_or_b64 exec, exec, s[38:39]
	v_cvt_f32_u32_e32 v4, v2
	buffer_inv sc1
	s_waitcnt vmcnt(1)
	v_readfirstlane_b32 s12, v3
	s_mov_b64 s[38:39], -1
	v_rcp_iflag_f32_e32 v4, v4
	v_add_u32_e32 v0, s12, v0
	v_add_u32_e32 v5, 1, v0
	v_readlane_b32 s12, v252, 14
	v_mul_f32_e32 v3, 0x4f7ffffe, v4
	v_cvt_u32_f32_e32 v3, v3
	v_sub_u32_e32 v4, 0, v2
	v_readlane_b32 s13, v252, 15
	v_mul_lo_u32 v4, v4, v3
	v_mul_hi_u32 v4, v3, v4
	v_add_u32_e32 v3, v3, v4
	v_mul_hi_u32 v3, v0, v3
	v_mul_lo_u32 v4, v3, v2
	v_sub_u32_e32 v0, v0, v4
	v_add_u32_e32 v6, 1, v3
	v_cmp_ge_u32_e32 vcc, v0, v2
	v_sub_u32_e32 v4, v0, v2
	s_nop 0
	v_cndmask_b32_e32 v3, v3, v6, vcc
	v_cndmask_b32_e32 v0, v0, v4, vcc
	v_add_u32_e32 v4, 1, v3
	v_cmp_ge_u32_e32 vcc, v0, v2
	s_nop 1
	v_cndmask_b32_e32 v0, v3, v4, vcc
	v_mul_lo_u32 v3, v2, v0
	v_add_u32_e32 v2, v3, v2
	v_cmp_ne_u32_e32 vcc, v5, v2
	v_mov_b64_e32 v[2:3], s[12:13]
	s_and_saveexec_b64 s[36:37], vcc
	s_cbranch_execz .LBB0_170
	v_readlane_b32 s12, v252, 14
	v_readlane_b32 s13, v252, 15
	s_mov_b64 s[40:41], 0
	s_nop 3
	global_load_dword v2, v1, s[12:13] sc1
	s_waitcnt vmcnt(0)
	v_cmp_eq_u32_e32 vcc, v2, v0
	s_and_saveexec_b64 s[38:39], vcc
	s_cbranch_execz .LBB0_169
	s_mov_b32 s12, 1
	s_branch .LBB0_162

; DI unsigned xb_add(unsigned* p, unsigned v) { return __hip_atomic_fetch_add(p, v, __ATOMIC_RELAXED, __HIP_MEMORY_SCOPE_AGENT); }
; DI void xcd_barrier(const XcdBarrier& b) {
;     ...
;             __builtin_amdgcn_fence(__ATOMIC_ACQUIRE, "agent");
;             xb_add(&bar[XB_XGEN(b.x)], 1u);
.LBB0_172:
	s_or_b64 exec, exec, s[36:37]
	s_mov_b64 s[36:37], exec
	v_mbcnt_lo_u32_b32 v0, s36, 0
	v_mbcnt_hi_u32_b32 v0, s37, v0
	v_cmp_eq_u32_e32 vcc, 0, v0
	s_waitcnt vmcnt(0)
	s_and_saveexec_b64 s[38:39], vcc
	s_cbranch_execz .LBB0_174
	s_bcnt1_i32_b64 s12, s[36:37]
	v_mov_b32_e32 v0, s12
	v_readlane_b32 s12, v252, 10
	v_readlane_b32 s13, v252, 11
	s_nop 4
	global_atomic_add v1, v0, s[12:13]

; DI unsigned xb_ld(unsigned* p)              { return __hip_atomic_load(p, __ATOMIC_RELAXED, __HIP_MEMORY_SCOPE_AGENT); }
; DI unsigned xb_add(unsigned* p, unsigned v) { return __hip_atomic_fetch_add(p, v, __ATOMIC_RELAXED, __HIP_MEMORY_SCOPE_AGENT); }
; #define XB_SPIN(cond, bar) do { unsigned _sp = 0; while (cond) { __builtin_amdgcn_s_sleep(1); \
;     if ((++_sp & 255u) == 0u) { if (xb_ld(&(bar)[XB_TMO])) break; if (_sp > XB_SPIN_CAP) { atomicAdd(&(bar)[XB_TMO], 1u); break; } } } } while (0)
; DI void xcd_barrier(const XcdBarrier& b) {
;     ...
;             const unsigned og = xb_add(&bar[XB_TOP], 1u);
;             const unsigned tg = og / nx;
;             if (og + 1u == (tg + 1u) * nx) xb_add(&bar[XB_TOPGEN], 1u);
;             else XB_SPIN(xb_ld(&bar[XB_TOPGEN]) == tg, bar);
.LBB0_413:
	s_or_b64 exec, exec, s[38:39]
	buffer_inv sc1
	s_waitcnt vmcnt(1)
	v_readfirstlane_b32 s12, v3
	v_sub_u32_e32 v4, 0, v2
	s_mov_b64 s[38:39], -1
	v_add_u32_e32 v3, s12, v0
	v_cvt_f32_u32_e32 v0, v2
	v_readlane_b32 s12, v252, 14
	v_readlane_b32 s13, v252, 15
	v_rcp_iflag_f32_e32 v0, v0
	s_nop 0
	v_mul_f32_e32 v0, 0x4f7ffffe, v0
	v_cvt_u32_f32_e32 v0, v0
	v_mul_lo_u32 v4, v4, v0
	v_mul_hi_u32 v4, v0, v4
	v_add_u32_e32 v0, v0, v4
	v_mul_hi_u32 v0, v3, v0
	v_mul_lo_u32 v4, v0, v2
	v_sub_u32_e32 v4, v3, v4
	v_cmp_ge_u32_e32 vcc, v4, v2
	v_add_u32_e32 v5, 1, v0
	v_add_u32_e32 v3, 1, v3
	v_cndmask_b32_e32 v0, v0, v5, vcc
	v_sub_u32_e32 v5, v4, v2
	v_cndmask_b32_e32 v4, v4, v5, vcc
	v_cmp_ge_u32_e32 vcc, v4, v2
	v_add_u32_e32 v4, 1, v0
	s_nop 0
	v_cndmask_b32_e32 v0, v0, v4, vcc
	v_mul_lo_u32 v4, v2, v0
	v_add_u32_e32 v2, v4, v2
	v_cmp_ne_u32_e32 vcc, v3, v2
	v_mov_b64_e32 v[2:3], s[12:13]
	s_and_saveexec_b64 s[36:37], vcc
	s_cbranch_execz .LBB0_425
	v_readlane_b32 s12, v252, 14
	v_readlane_b32 s13, v252, 15
	s_mov_b64 s[40:41], 0
	s_nop 3
	global_load_dword v2, v1, s[12:13] sc1
	s_waitcnt vmcnt(0)
	v_cmp_eq_u32_e32 vcc, v2, v0
	s_and_saveexec_b64 s[38:39], vcc
	s_cbranch_execz .LBB0_424
	s_mov_b32 s12, 1
	s_branch .LBB0_417

; DI unsigned xb_add(unsigned* p, unsigned v) { return __hip_atomic_fetch_add(p, v, __ATOMIC_RELAXED, __HIP_MEMORY_SCOPE_AGENT); }
; DI void xcd_barrier(const XcdBarrier& b) {
;     ...
;             __builtin_amdgcn_fence(__ATOMIC_ACQUIRE, "agent");
;             xb_add(&bar[XB_XGEN(b.x)], 1u);
.LBB0_1512:
	s_or_b64 exec, exec, s[36:37]
	s_mov_b64 s[36:37], exec
	v_mbcnt_lo_u32_b32 v0, s36, 0
	v_mbcnt_hi_u32_b32 v0, s37, v0
	v_cmp_eq_u32_e32 vcc, 0, v0
	s_waitcnt vmcnt(0)
	s_and_saveexec_b64 s[38:39], vcc
	s_cbranch_execnz .LBB0_1513
	s_getpc_b64 s[98:99]
